# NSA top-k bit loops rewritten (pipelined masks, one SALU crossing per bit); compressed-branch pass 2 fast path
# speedup vs baseline: 1.0032x; 1.0029x over previous
.LBB0_268:
	s_lshl_b32 s0, s2, 6
	s_or_b32 s26, s0, s24
	s_lshl_b32 s0, s26, 4
	s_or_b32 s0, s0, 28
	v_cmp_le_i32_e32 vcc, s0, v176
	s_and_saveexec_b64 s[16:17], vcc
	s_cbranch_execz .LBB0_267
	s_mul_i32 s25, s2, 0x2400
	v_readfirstlane_b32 s1, v176
	s_add_i32 s3, s0, 0x3f3
	s_cmp_le_i32 s3, s1
	s_cbranch_scc0 .Lnsa_cmp2_slow
	v_add_u32_e32 v1, s25, v3
	v_add_u32_e32 v2, s25, v8
	ds_read_b128 v[180:183], v1
	ds_read_b128 v[184:187], v1 offset:4608
	ds_read_b128 v[188:191], v1 offset:32
	ds_read_b128 v[192:195], v1 offset:4640
	ds_read_b128 v[196:199], v1 offset:64
	ds_read_b128 v[200:203], v1 offset:4672
	ds_read_b128 v[204:207], v1 offset:96
	ds_read_b128 v[208:211], v1 offset:4704
	v_mul_f32_e64 v222, -1.0, s80
	v_mov_b32_e32 v220, 0x3e38aa3b
	v_lshl_add_u32 v15, s26, 2, v173
	s_waitcnt lgkmcnt(6)
	v_mfma_f32_32x32x16_bf16 v[48:63], v[180:183], v[80:83], 0
	v_mfma_f32_32x32x16_bf16 v[64:79], v[184:187], v[80:83], 0
	s_waitcnt lgkmcnt(4)
	v_mfma_f32_32x32x16_bf16 v[48:63], v[188:191], v[84:87], v[48:63]
	v_mfma_f32_32x32x16_bf16 v[64:79], v[192:195], v[84:87], v[64:79]
	s_waitcnt lgkmcnt(2)
	v_mfma_f32_32x32x16_bf16 v[48:63], v[196:199], v[88:91], v[48:63]
	v_mfma_f32_32x32x16_bf16 v[64:79], v[200:203], v[88:91], v[64:79]
	s_waitcnt lgkmcnt(0)
	v_mfma_f32_32x32x16_bf16 v[48:63], v[204:207], v[92:95], v[48:63]
	v_mfma_f32_32x32x16_bf16 v[64:79], v[208:211], v[92:95], v[64:79]
	ds_read_b64_tr_b16 v[212:213], v2 offset:18432
	ds_read_b64_tr_b16 v[214:215], v2 offset:19584
	ds_read_b64_tr_b16 v[216:217], v2 offset:18496
	ds_read_b64_tr_b16 v[218:219], v2 offset:19648
	ds_read_b64_tr_b16 v[236:237], v2 offset:20736
	ds_read_b64_tr_b16 v[238:239], v2 offset:21888
	ds_read_b64_tr_b16 v[240:241], v2 offset:20800
	ds_read_b64_tr_b16 v[242:243], v2 offset:21952
	s_nop 7
	s_nop 3
	v_pk_fma_f32 v[48:49], v[48:49], v[220:221], v[222:223] op_sel_hi:[1,0,0]
	v_pk_fma_f32 v[50:51], v[50:51], v[220:221], v[222:223] op_sel_hi:[1,0,0]
	v_pk_fma_f32 v[52:53], v[52:53], v[220:221], v[222:223] op_sel_hi:[1,0,0]
	v_pk_fma_f32 v[54:55], v[54:55], v[220:221], v[222:223] op_sel_hi:[1,0,0]
	v_pk_fma_f32 v[56:57], v[56:57], v[220:221], v[222:223] op_sel_hi:[1,0,0]
	v_pk_fma_f32 v[58:59], v[58:59], v[220:221], v[222:223] op_sel_hi:[1,0,0]
	v_pk_fma_f32 v[60:61], v[60:61], v[220:221], v[222:223] op_sel_hi:[1,0,0]
	v_pk_fma_f32 v[62:63], v[62:63], v[220:221], v[222:223] op_sel_hi:[1,0,0]
	v_exp_f32_e32 v48, v48
	v_exp_f32_e32 v49, v49
	v_exp_f32_e32 v50, v50
	v_exp_f32_e32 v51, v51
	v_exp_f32_e32 v52, v52
	v_exp_f32_e32 v53, v53
	v_exp_f32_e32 v54, v54
	v_exp_f32_e32 v55, v55
	v_exp_f32_e32 v56, v56
	v_exp_f32_e32 v57, v57
	v_exp_f32_e32 v58, v58
	v_exp_f32_e32 v59, v59
	v_exp_f32_e32 v60, v60
	v_exp_f32_e32 v61, v61
	v_exp_f32_e32 v62, v62
	v_exp_f32_e32 v63, v63
	v_pk_fma_f32 v[64:65], v[64:65], v[220:221], v[222:223] op_sel_hi:[1,0,0]
	v_pk_fma_f32 v[66:67], v[66:67], v[220:221], v[222:223] op_sel_hi:[1,0,0]
	v_pk_fma_f32 v[68:69], v[68:69], v[220:221], v[222:223] op_sel_hi:[1,0,0]
	v_pk_fma_f32 v[70:71], v[70:71], v[220:221], v[222:223] op_sel_hi:[1,0,0]
	v_pk_fma_f32 v[72:73], v[72:73], v[220:221], v[222:223] op_sel_hi:[1,0,0]
	v_pk_fma_f32 v[74:75], v[74:75], v[220:221], v[222:223] op_sel_hi:[1,0,0]
	v_pk_fma_f32 v[76:77], v[76:77], v[220:221], v[222:223] op_sel_hi:[1,0,0]
	v_pk_fma_f32 v[78:79], v[78:79], v[220:221], v[222:223] op_sel_hi:[1,0,0]
	v_exp_f32_e32 v64, v64
	v_exp_f32_e32 v65, v65
	v_exp_f32_e32 v66, v66
	v_exp_f32_e32 v67, v67
	v_exp_f32_e32 v68, v68
	v_exp_f32_e32 v69, v69
	v_exp_f32_e32 v70, v70
	v_exp_f32_e32 v71, v71
	v_exp_f32_e32 v72, v72
	v_exp_f32_e32 v73, v73
	v_exp_f32_e32 v74, v74
	v_exp_f32_e32 v75, v75
	v_exp_f32_e32 v76, v76
	v_exp_f32_e32 v77, v77
	v_exp_f32_e32 v78, v78
	v_exp_f32_e32 v79, v79
	v_pk_mul_f32 v[48:49], v[48:49], v[102:103]
	v_pk_mul_f32 v[50:51], v[50:51], v[102:103]
	v_pk_mul_f32 v[52:53], v[52:53], v[102:103]
	v_pk_mul_f32 v[54:55], v[54:55], v[102:103]
	v_pk_mul_f32 v[56:57], v[56:57], v[102:103]
	v_pk_mul_f32 v[58:59], v[58:59], v[102:103]
	v_pk_mul_f32 v[60:61], v[60:61], v[102:103]
	v_pk_mul_f32 v[62:63], v[62:63], v[102:103]
	v_pk_mul_f32 v[64:65], v[64:65], v[102:103]
	v_pk_mul_f32 v[66:67], v[66:67], v[102:103]
	v_pk_mul_f32 v[68:69], v[68:69], v[102:103]
	v_pk_mul_f32 v[70:71], v[70:71], v[102:103]
	v_pk_mul_f32 v[72:73], v[72:73], v[102:103]
	v_pk_mul_f32 v[74:75], v[74:75], v[102:103]
	v_pk_mul_f32 v[76:77], v[76:77], v[102:103]
	v_pk_mul_f32 v[78:79], v[78:79], v[102:103]
	v_add_f32_dpp v180, v48, v48 row_half_mirror row_mask:0xf bank_mask:0xf bound_ctrl:1
	v_add_f32_dpp v181, v49, v49 row_half_mirror row_mask:0xf bank_mask:0xf bound_ctrl:1
	v_add_f32_dpp v182, v50, v50 row_half_mirror row_mask:0xf bank_mask:0xf bound_ctrl:1
	v_add_f32_dpp v183, v51, v51 row_half_mirror row_mask:0xf bank_mask:0xf bound_ctrl:1
	v_add_f32_dpp v184, v52, v52 row_half_mirror row_mask:0xf bank_mask:0xf bound_ctrl:1
	v_add_f32_dpp v185, v53, v53 row_half_mirror row_mask:0xf bank_mask:0xf bound_ctrl:1
	v_add_f32_dpp v186, v54, v54 row_half_mirror row_mask:0xf bank_mask:0xf bound_ctrl:1
	v_add_f32_dpp v187, v55, v55 row_half_mirror row_mask:0xf bank_mask:0xf bound_ctrl:1
	v_add_f32_dpp v180, v180, v180 quad_perm:[1,0,3,2] row_mask:0xf bank_mask:0xf bound_ctrl:1
	v_add_f32_dpp v181, v181, v181 quad_perm:[1,0,3,2] row_mask:0xf bank_mask:0xf bound_ctrl:1
	v_add_f32_dpp v182, v182, v182 quad_perm:[1,0,3,2] row_mask:0xf bank_mask:0xf bound_ctrl:1
	v_add_f32_dpp v183, v183, v183 quad_perm:[1,0,3,2] row_mask:0xf bank_mask:0xf bound_ctrl:1
	v_add_f32_dpp v184, v184, v184 quad_perm:[1,0,3,2] row_mask:0xf bank_mask:0xf bound_ctrl:1
	v_add_f32_dpp v185, v185, v185 quad_perm:[1,0,3,2] row_mask:0xf bank_mask:0xf bound_ctrl:1
	v_add_f32_dpp v186, v186, v186 quad_perm:[1,0,3,2] row_mask:0xf bank_mask:0xf bound_ctrl:1
	v_add_f32_dpp v187, v187, v187 quad_perm:[1,0,3,2] row_mask:0xf bank_mask:0xf bound_ctrl:1
	v_add_f32_dpp v180, v180, v180 quad_perm:[2,3,0,1] row_mask:0xf bank_mask:0xf bound_ctrl:1
	v_add_f32_dpp v181, v181, v181 quad_perm:[2,3,0,1] row_mask:0xf bank_mask:0xf bound_ctrl:1
	v_add_f32_dpp v182, v182, v182 quad_perm:[2,3,0,1] row_mask:0xf bank_mask:0xf bound_ctrl:1
	v_add_f32_dpp v183, v183, v183 quad_perm:[2,3,0,1] row_mask:0xf bank_mask:0xf bound_ctrl:1
	v_add_f32_dpp v184, v184, v184 quad_perm:[2,3,0,1] row_mask:0xf bank_mask:0xf bound_ctrl:1
	v_add_f32_dpp v185, v185, v185 quad_perm:[2,3,0,1] row_mask:0xf bank_mask:0xf bound_ctrl:1
	v_add_f32_dpp v186, v186, v186 quad_perm:[2,3,0,1] row_mask:0xf bank_mask:0xf bound_ctrl:1
	v_add_f32_dpp v187, v187, v187 quad_perm:[2,3,0,1] row_mask:0xf bank_mask:0xf bound_ctrl:1
	v_add_f32_dpp v188, v56, v56 row_half_mirror row_mask:0xf bank_mask:0xf bound_ctrl:1
	v_add_f32_dpp v189, v57, v57 row_half_mirror row_mask:0xf bank_mask:0xf bound_ctrl:1
	v_add_f32_dpp v190, v58, v58 row_half_mirror row_mask:0xf bank_mask:0xf bound_ctrl:1
	v_add_f32_dpp v191, v59, v59 row_half_mirror row_mask:0xf bank_mask:0xf bound_ctrl:1
	v_add_f32_dpp v192, v60, v60 row_half_mirror row_mask:0xf bank_mask:0xf bound_ctrl:1
	v_add_f32_dpp v193, v61, v61 row_half_mirror row_mask:0xf bank_mask:0xf bound_ctrl:1
	v_add_f32_dpp v194, v62, v62 row_half_mirror row_mask:0xf bank_mask:0xf bound_ctrl:1
	v_add_f32_dpp v195, v63, v63 row_half_mirror row_mask:0xf bank_mask:0xf bound_ctrl:1
	v_add_f32_dpp v188, v188, v188 quad_perm:[1,0,3,2] row_mask:0xf bank_mask:0xf bound_ctrl:1
	v_add_f32_dpp v189, v189, v189 quad_perm:[1,0,3,2] row_mask:0xf bank_mask:0xf bound_ctrl:1
	v_add_f32_dpp v190, v190, v190 quad_perm:[1,0,3,2] row_mask:0xf bank_mask:0xf bound_ctrl:1
	v_add_f32_dpp v191, v191, v191 quad_perm:[1,0,3,2] row_mask:0xf bank_mask:0xf bound_ctrl:1
	v_add_f32_dpp v192, v192, v192 quad_perm:[1,0,3,2] row_mask:0xf bank_mask:0xf bound_ctrl:1
	v_add_f32_dpp v193, v193, v193 quad_perm:[1,0,3,2] row_mask:0xf bank_mask:0xf bound_ctrl:1
	v_add_f32_dpp v194, v194, v194 quad_perm:[1,0,3,2] row_mask:0xf bank_mask:0xf bound_ctrl:1
	v_add_f32_dpp v195, v195, v195 quad_perm:[1,0,3,2] row_mask:0xf bank_mask:0xf bound_ctrl:1
	v_add_f32_dpp v188, v188, v188 quad_perm:[2,3,0,1] row_mask:0xf bank_mask:0xf bound_ctrl:1
	v_add_f32_dpp v189, v189, v189 quad_perm:[2,3,0,1] row_mask:0xf bank_mask:0xf bound_ctrl:1
	v_add_f32_dpp v190, v190, v190 quad_perm:[2,3,0,1] row_mask:0xf bank_mask:0xf bound_ctrl:1
	v_add_f32_dpp v191, v191, v191 quad_perm:[2,3,0,1] row_mask:0xf bank_mask:0xf bound_ctrl:1
	v_add_f32_dpp v192, v192, v192 quad_perm:[2,3,0,1] row_mask:0xf bank_mask:0xf bound_ctrl:1
	v_add_f32_dpp v193, v193, v193 quad_perm:[2,3,0,1] row_mask:0xf bank_mask:0xf bound_ctrl:1
	v_add_f32_dpp v194, v194, v194 quad_perm:[2,3,0,1] row_mask:0xf bank_mask:0xf bound_ctrl:1
	v_add_f32_dpp v195, v195, v195 quad_perm:[2,3,0,1] row_mask:0xf bank_mask:0xf bound_ctrl:1
	v_add_f32_dpp v196, v64, v64 row_half_mirror row_mask:0xf bank_mask:0xf bound_ctrl:1
	v_add_f32_dpp v197, v65, v65 row_half_mirror row_mask:0xf bank_mask:0xf bound_ctrl:1
	v_add_f32_dpp v198, v66, v66 row_half_mirror row_mask:0xf bank_mask:0xf bound_ctrl:1
	v_add_f32_dpp v199, v67, v67 row_half_mirror row_mask:0xf bank_mask:0xf bound_ctrl:1
	v_add_f32_dpp v200, v68, v68 row_half_mirror row_mask:0xf bank_mask:0xf bound_ctrl:1
	v_add_f32_dpp v201, v69, v69 row_half_mirror row_mask:0xf bank_mask:0xf bound_ctrl:1
	v_add_f32_dpp v202, v70, v70 row_half_mirror row_mask:0xf bank_mask:0xf bound_ctrl:1
	v_add_f32_dpp v203, v71, v71 row_half_mirror row_mask:0xf bank_mask:0xf bound_ctrl:1
	v_add_f32_dpp v196, v196, v196 quad_perm:[1,0,3,2] row_mask:0xf bank_mask:0xf bound_ctrl:1
	v_add_f32_dpp v197, v197, v197 quad_perm:[1,0,3,2] row_mask:0xf bank_mask:0xf bound_ctrl:1
	v_add_f32_dpp v198, v198, v198 quad_perm:[1,0,3,2] row_mask:0xf bank_mask:0xf bound_ctrl:1
	v_add_f32_dpp v199, v199, v199 quad_perm:[1,0,3,2] row_mask:0xf bank_mask:0xf bound_ctrl:1
	v_add_f32_dpp v200, v200, v200 quad_perm:[1,0,3,2] row_mask:0xf bank_mask:0xf bound_ctrl:1
	v_add_f32_dpp v201, v201, v201 quad_perm:[1,0,3,2] row_mask:0xf bank_mask:0xf bound_ctrl:1
	v_add_f32_dpp v202, v202, v202 quad_perm:[1,0,3,2] row_mask:0xf bank_mask:0xf bound_ctrl:1
	v_add_f32_dpp v203, v203, v203 quad_perm:[1,0,3,2] row_mask:0xf bank_mask:0xf bound_ctrl:1
	v_add_f32_dpp v196, v196, v196 quad_perm:[2,3,0,1] row_mask:0xf bank_mask:0xf bound_ctrl:1
	v_add_f32_dpp v197, v197, v197 quad_perm:[2,3,0,1] row_mask:0xf bank_mask:0xf bound_ctrl:1
	v_add_f32_dpp v198, v198, v198 quad_perm:[2,3,0,1] row_mask:0xf bank_mask:0xf bound_ctrl:1
	v_add_f32_dpp v199, v199, v199 quad_perm:[2,3,0,1] row_mask:0xf bank_mask:0xf bound_ctrl:1
	v_add_f32_dpp v200, v200, v200 quad_perm:[2,3,0,1] row_mask:0xf bank_mask:0xf bound_ctrl:1
	v_add_f32_dpp v201, v201, v201 quad_perm:[2,3,0,1] row_mask:0xf bank_mask:0xf bound_ctrl:1
	v_add_f32_dpp v202, v202, v202 quad_perm:[2,3,0,1] row_mask:0xf bank_mask:0xf bound_ctrl:1
	v_add_f32_dpp v203, v203, v203 quad_perm:[2,3,0,1] row_mask:0xf bank_mask:0xf bound_ctrl:1
	v_add_f32_dpp v204, v72, v72 row_half_mirror row_mask:0xf bank_mask:0xf bound_ctrl:1
	v_add_f32_dpp v205, v73, v73 row_half_mirror row_mask:0xf bank_mask:0xf bound_ctrl:1
	v_add_f32_dpp v206, v74, v74 row_half_mirror row_mask:0xf bank_mask:0xf bound_ctrl:1
	v_add_f32_dpp v207, v75, v75 row_half_mirror row_mask:0xf bank_mask:0xf bound_ctrl:1
	v_add_f32_dpp v208, v76, v76 row_half_mirror row_mask:0xf bank_mask:0xf bound_ctrl:1
	v_add_f32_dpp v209, v77, v77 row_half_mirror row_mask:0xf bank_mask:0xf bound_ctrl:1
	v_add_f32_dpp v210, v78, v78 row_half_mirror row_mask:0xf bank_mask:0xf bound_ctrl:1
	v_add_f32_dpp v211, v79, v79 row_half_mirror row_mask:0xf bank_mask:0xf bound_ctrl:1
	v_add_f32_dpp v204, v204, v204 quad_perm:[1,0,3,2] row_mask:0xf bank_mask:0xf bound_ctrl:1
	v_add_f32_dpp v205, v205, v205 quad_perm:[1,0,3,2] row_mask:0xf bank_mask:0xf bound_ctrl:1
	v_add_f32_dpp v206, v206, v206 quad_perm:[1,0,3,2] row_mask:0xf bank_mask:0xf bound_ctrl:1
	v_add_f32_dpp v207, v207, v207 quad_perm:[1,0,3,2] row_mask:0xf bank_mask:0xf bound_ctrl:1
	v_add_f32_dpp v208, v208, v208 quad_perm:[1,0,3,2] row_mask:0xf bank_mask:0xf bound_ctrl:1
	v_add_f32_dpp v209, v209, v209 quad_perm:[1,0,3,2] row_mask:0xf bank_mask:0xf bound_ctrl:1
	v_add_f32_dpp v210, v210, v210 quad_perm:[1,0,3,2] row_mask:0xf bank_mask:0xf bound_ctrl:1
	v_add_f32_dpp v211, v211, v211 quad_perm:[1,0,3,2] row_mask:0xf bank_mask:0xf bound_ctrl:1
	v_add_f32_dpp v204, v204, v204 quad_perm:[2,3,0,1] row_mask:0xf bank_mask:0xf bound_ctrl:1
	v_add_f32_dpp v205, v205, v205 quad_perm:[2,3,0,1] row_mask:0xf bank_mask:0xf bound_ctrl:1
	v_add_f32_dpp v206, v206, v206 quad_perm:[2,3,0,1] row_mask:0xf bank_mask:0xf bound_ctrl:1
	v_add_f32_dpp v207, v207, v207 quad_perm:[2,3,0,1] row_mask:0xf bank_mask:0xf bound_ctrl:1
	v_add_f32_dpp v208, v208, v208 quad_perm:[2,3,0,1] row_mask:0xf bank_mask:0xf bound_ctrl:1
	v_add_f32_dpp v209, v209, v209 quad_perm:[2,3,0,1] row_mask:0xf bank_mask:0xf bound_ctrl:1
	v_add_f32_dpp v210, v210, v210 quad_perm:[2,3,0,1] row_mask:0xf bank_mask:0xf bound_ctrl:1
	v_add_f32_dpp v211, v211, v211 quad_perm:[2,3,0,1] row_mask:0xf bank_mask:0xf bound_ctrl:1
	s_and_saveexec_b64 s[0:1], s[36:37]
	ds_write2_b32 v15, v180, v196 offset0:0 offset1:32
	ds_write2_b32 v15, v181, v197 offset0:1 offset1:33
	ds_write2_b32 v15, v182, v198 offset0:2 offset1:34
	ds_write2_b32 v15, v183, v199 offset0:3 offset1:35
	ds_write2_b32 v15, v184, v200 offset0:8 offset1:40
	ds_write2_b32 v15, v185, v201 offset0:9 offset1:41
	ds_write2_b32 v15, v186, v202 offset0:10 offset1:42
	ds_write2_b32 v15, v187, v203 offset0:11 offset1:43
	ds_write2_b32 v15, v188, v204 offset0:16 offset1:48
	ds_write2_b32 v15, v189, v205 offset0:17 offset1:49
	ds_write2_b32 v15, v190, v206 offset0:18 offset1:50
	ds_write2_b32 v15, v191, v207 offset0:19 offset1:51
	ds_write2_b32 v15, v192, v208 offset0:24 offset1:56
	ds_write2_b32 v15, v193, v209 offset0:25 offset1:57
	ds_write2_b32 v15, v194, v210 offset0:26 offset1:58
	ds_write2_b32 v15, v195, v211 offset0:27 offset1:59
	s_or_b64 exec, exec, s[0:1]
	v_cvt_pk_bf16_f32 v48, v48, v49
	v_cvt_pk_bf16_f32 v49, v50, v51
	v_cvt_pk_bf16_f32 v50, v52, v53
	v_cvt_pk_bf16_f32 v51, v54, v55
	v_cvt_pk_bf16_f32 v56, v56, v57
	v_cvt_pk_bf16_f32 v57, v58, v59
	v_cvt_pk_bf16_f32 v58, v60, v61
	v_cvt_pk_bf16_f32 v59, v62, v63
	v_cvt_pk_bf16_f32 v64, v64, v65
	v_cvt_pk_bf16_f32 v65, v66, v67
	v_cvt_pk_bf16_f32 v66, v68, v69
	v_cvt_pk_bf16_f32 v67, v70, v71
	v_cvt_pk_bf16_f32 v72, v72, v73
	v_cvt_pk_bf16_f32 v73, v74, v75
	v_cvt_pk_bf16_f32 v74, v76, v77
	v_cvt_pk_bf16_f32 v75, v78, v79
	s_waitcnt lgkmcnt(0)
	v_mfma_f32_32x32x16_bf16 v[32:47], v[212:215], v[48:51], v[32:47]
	ds_read_b64_tr_b16 v[244:245], v2 offset:23040
	ds_read_b64_tr_b16 v[246:247], v2 offset:24192
	s_waitcnt lgkmcnt(6)
	v_mfma_f32_32x32x16_bf16 v[16:31], v[216:219], v[48:51], v[16:31]
	ds_read_b64_tr_b16 v[248:249], v2 offset:23104
	ds_read_b64_tr_b16 v[250:251], v2 offset:24256
	s_waitcnt lgkmcnt(6)
	v_mfma_f32_32x32x16_bf16 v[32:47], v[236:239], v[56:59], v[32:47]
	ds_read_b64_tr_b16 v[212:213], v2 offset:25344
	ds_read_b64_tr_b16 v[214:215], v2 offset:26496
	s_waitcnt lgkmcnt(6)
	v_mfma_f32_32x32x16_bf16 v[16:31], v[240:243], v[56:59], v[16:31]
	ds_read_b64_tr_b16 v[216:217], v2 offset:25408
	ds_read_b64_tr_b16 v[218:219], v2 offset:26560
	s_waitcnt lgkmcnt(6)
	v_mfma_f32_32x32x16_bf16 v[32:47], v[244:247], v[64:67], v[32:47]
	s_waitcnt lgkmcnt(4)
	v_mfma_f32_32x32x16_bf16 v[16:31], v[248:251], v[64:67], v[16:31]
	s_waitcnt lgkmcnt(2)
	v_mfma_f32_32x32x16_bf16 v[32:47], v[212:215], v[72:75], v[32:47]
	s_waitcnt lgkmcnt(0)
	v_mfma_f32_32x32x16_bf16 v[16:31], v[216:219], v[72:75], v[16:31]
	s_branch .LBB0_267
.Lnsa_cmp2_slow:
	v_add_u32_e32 v1, s25, v3
	ds_read_b128 v[4:7], v1
	v_mov_b32_e32 v9, s80
	v_lshl_add_u32 v15, s26, 2, v173
	s_waitcnt lgkmcnt(0)
	v_mfma_f32_32x32x16_bf16 v[64:79], v[4:7], v[80:83], 0
	ds_read_b128 v[4:7], v1 offset:4608
	s_waitcnt lgkmcnt(0)
	v_mfma_f32_32x32x16_bf16 v[48:63], v[4:7], v[80:83], 0
	ds_read_b128 v[4:7], v1 offset:32
	s_waitcnt lgkmcnt(0)
	v_mfma_f32_32x32x16_bf16 v[64:79], v[4:7], v[84:87], v[64:79]
	ds_read_b128 v[4:7], v1 offset:4640
	s_waitcnt lgkmcnt(0)
	v_mfma_f32_32x32x16_bf16 v[48:63], v[4:7], v[84:87], v[48:63]
	ds_read_b128 v[4:7], v1 offset:64
	s_waitcnt lgkmcnt(0)
	v_mfma_f32_32x32x16_bf16 v[64:79], v[4:7], v[88:91], v[64:79]
	ds_read_b128 v[4:7], v1 offset:4672
	s_waitcnt lgkmcnt(0)
	v_mfma_f32_32x32x16_bf16 v[48:63], v[4:7], v[88:91], v[48:63]
	ds_read_b128 v[4:7], v1 offset:96
	s_waitcnt lgkmcnt(0)
	v_mfma_f32_32x32x16_bf16 v[64:79], v[4:7], v[92:95], v[64:79]
	ds_read_b128 v[4:7], v1 offset:4704
	v_or_b32_e32 v1, s26, v116
	v_lshlrev_b32_e32 v2, 4, v1
	v_or_b32_e32 v12, 31, v2
	v_cmp_le_i32_e64 s[0:1], v12, v122
	s_nop 6
	v_fma_f32 v1, v64, s33, -v9
	s_waitcnt lgkmcnt(0)
	v_mfma_f32_32x32x16_bf16 v[48:63], v[4:7], v[92:95], v[48:63]
	v_exp_f32_e32 v10, v1
	v_or_b32_e32 v7, 47, v2
	v_cmp_le_i32_e32 vcc, v7, v97
	s_nop 8
	v_fma_f32 v1, v48, s33, -v9
	v_exp_f32_e32 v6, v1
	v_fma_f32 v1, v65, s33, -v9
	v_fma_f32 v7, v49, s33, -v9
	v_exp_f32_e32 v11, v1
	v_exp_f32_e32 v7, v7
	v_or_b32_e32 v9, 0x21f, v2
	v_cmp_le_i32_e64 s[2:3], v9, v122
	v_pk_mul_f32 v[4:5], v[102:103], v[10:11]
	v_pk_mul_f32 v[6:7], v[102:103], v[6:7]
	v_cndmask_b32_e64 v13, 0, v4, s[0:1]
	v_or_b32_e32 v4, 0x22f, v2
	v_cndmask_b32_e64 v9, 0, v6, s[2:3]
	v_cmp_le_i32_e64 s[0:1], v4, v97
	v_add_f32_dpp v4, v13, v13 row_half_mirror row_mask:0xf bank_mask:0xf bound_ctrl:1
	v_add_f32_dpp v10, v9, v9 row_half_mirror row_mask:0xf bank_mask:0xf bound_ctrl:1
	v_mov_b32_e32 v1, v2
	v_add_f32_dpp v4, v4, v4 quad_perm:[1,0,3,2] row_mask:0xf bank_mask:0xf bound_ctrl:1
	v_add_f32_dpp v10, v10, v10 quad_perm:[1,0,3,2] row_mask:0xf bank_mask:0xf bound_ctrl:1
	s_nop 0
	v_mov_b32_dpp v6, v4 quad_perm:[2,3,0,1] row_mask:0xf bank_mask:0xf bound_ctrl:1
	v_mov_b32_dpp v11, v10 quad_perm:[2,3,0,1] row_mask:0xf bank_mask:0xf bound_ctrl:1
	s_and_saveexec_b64 s[2:3], s[36:37]
	v_add_f32_e32 v4, v4, v6
	v_add_f32_e32 v6, v10, v11
	ds_write2_b32 v15, v4, v6 offset1:32
	s_or_b64 exec, exec, s[2:3]
	v_cndmask_b32_e32 v49, 0, v5, vcc
	v_cndmask_b32_e64 v10, 0, v7, s[0:1]
	s_nop 0
	v_add_f32_dpp v4, v49, v49 row_half_mirror row_mask:0xf bank_mask:0xf bound_ctrl:1
	v_add_f32_dpp v6, v10, v10 row_half_mirror row_mask:0xf bank_mask:0xf bound_ctrl:1
	s_nop 0
	v_add_f32_dpp v4, v4, v4 quad_perm:[1,0,3,2] row_mask:0xf bank_mask:0xf bound_ctrl:1
	v_add_f32_dpp v6, v6, v6 quad_perm:[1,0,3,2] row_mask:0xf bank_mask:0xf bound_ctrl:1
	s_nop 0
	v_mov_b32_dpp v5, v4 quad_perm:[2,3,0,1] row_mask:0xf bank_mask:0xf bound_ctrl:1
	v_mov_b32_dpp v7, v6 quad_perm:[2,3,0,1] row_mask:0xf bank_mask:0xf bound_ctrl:1
	s_and_saveexec_b64 s[0:1], s[36:37]
	v_add_f32_e32 v4, v4, v5
	v_add_f32_e32 v5, v6, v7
	ds_write2_b32 v15, v4, v5 offset0:1 offset1:33
	s_or_b64 exec, exec, s[0:1]
	v_mov_b32_e32 v4, s80
	v_fma_f32 v5, v66, s33, -v4
	v_exp_f32_e32 v5, v5
	v_fma_f32 v4, v50, s33, -v4
	v_exp_f32_e32 v4, v4
	v_or_b32_e32 v6, 63, v2
	v_mul_f32_e32 v5, v102, v5
	v_cmp_le_i32_e32 vcc, v6, v122
	v_mul_f32_e32 v4, v102, v4
	s_nop 0
	v_cndmask_b32_e32 v64, 0, v5, vcc
	v_or_b32_e32 v5, 0x23f, v2
	v_cmp_le_i32_e32 vcc, v5, v122
	s_nop 1
	v_cndmask_b32_e32 v11, 0, v4, vcc
	v_add_f32_dpp v4, v64, v64 row_half_mirror row_mask:0xf bank_mask:0xf bound_ctrl:1
	s_nop 0
	v_add_f32_dpp v6, v11, v11 row_half_mirror row_mask:0xf bank_mask:0xf bound_ctrl:1
	v_add_f32_dpp v4, v4, v4 quad_perm:[1,0,3,2] row_mask:0xf bank_mask:0xf bound_ctrl:1
	s_nop 0
	v_add_f32_dpp v6, v6, v6 quad_perm:[1,0,3,2] row_mask:0xf bank_mask:0xf bound_ctrl:1
	v_mov_b32_dpp v5, v4 quad_perm:[2,3,0,1] row_mask:0xf bank_mask:0xf bound_ctrl:1
	s_nop 0
	v_mov_b32_dpp v7, v6 quad_perm:[2,3,0,1] row_mask:0xf bank_mask:0xf bound_ctrl:1
	s_and_saveexec_b64 s[0:1], s[36:37]
	v_add_f32_e32 v4, v4, v5
	v_add_f32_e32 v5, v6, v7
	ds_write2_b32 v15, v4, v5 offset0:2 offset1:34
	s_or_b64 exec, exec, s[0:1]
	v_mov_b32_e32 v4, s80
	v_fma_f32 v5, v67, s33, -v4
	v_exp_f32_e32 v5, v5
	v_fma_f32 v4, v51, s33, -v4
	v_exp_f32_e32 v4, v4
	v_add_u32_e32 v6, 0x4f, v2
	v_mul_f32_e32 v5, v102, v5
	v_cmp_le_i32_e32 vcc, v6, v122
	v_mul_f32_e32 v4, v102, v4
	s_nop 0
	v_cndmask_b32_e32 v65, 0, v5, vcc
	v_add_u32_e32 v5, 0x24f, v2
	v_cmp_le_i32_e32 vcc, v5, v122
	s_nop 1
	v_cndmask_b32_e32 v12, 0, v4, vcc
	v_add_f32_dpp v4, v65, v65 row_half_mirror row_mask:0xf bank_mask:0xf bound_ctrl:1
	s_nop 0
	v_add_f32_dpp v6, v12, v12 row_half_mirror row_mask:0xf bank_mask:0xf bound_ctrl:1
	v_add_f32_dpp v4, v4, v4 quad_perm:[1,0,3,2] row_mask:0xf bank_mask:0xf bound_ctrl:1
	s_nop 0
	v_add_f32_dpp v6, v6, v6 quad_perm:[1,0,3,2] row_mask:0xf bank_mask:0xf bound_ctrl:1
	v_mov_b32_dpp v5, v4 quad_perm:[2,3,0,1] row_mask:0xf bank_mask:0xf bound_ctrl:1
	s_nop 0
	v_mov_b32_dpp v7, v6 quad_perm:[2,3,0,1] row_mask:0xf bank_mask:0xf bound_ctrl:1
	s_and_saveexec_b64 s[0:1], s[36:37]
	v_add_f32_e32 v4, v4, v5
	v_add_f32_e32 v5, v6, v7
	ds_write2_b32 v15, v4, v5 offset0:3 offset1:35
	s_or_b64 exec, exec, s[0:1]
	v_mov_b32_e32 v7, s80
	v_fma_f32 v4, v68, s33, -v7
	v_fma_f32 v6, v52, s33, -v7
	v_fma_f32 v5, v69, s33, -v7
	v_fma_f32 v7, v53, s33, -v7
	v_exp_f32_e32 v4, v4
	v_exp_f32_e32 v5, v5
	v_exp_f32_e32 v6, v6
	v_exp_f32_e32 v7, v7
	v_or_b32_e32 v14, 0xaf, v1
	v_or_b32_e32 v48, 0x9f, v2
	v_cmp_le_i32_e32 vcc, v14, v97
	v_or_b32_e32 v14, 0x29f, v2
	v_pk_mul_f32 v[4:5], v[102:103], v[4:5]
	v_cmp_le_i32_e64 s[0:1], v48, v122
	v_pk_mul_f32 v[6:7], v[102:103], v[6:7]
	v_cmp_le_i32_e64 s[2:3], v14, v122
	v_cndmask_b32_e64 v66, 0, v4, s[0:1]
	v_or_b32_e32 v4, 0x2af, v1
	v_cndmask_b32_e64 v14, 0, v6, s[2:3]
	v_cmp_le_i32_e64 s[0:1], v4, v97
	v_add_f32_dpp v4, v66, v66 row_half_mirror row_mask:0xf bank_mask:0xf bound_ctrl:1
	v_add_f32_dpp v48, v14, v14 row_half_mirror row_mask:0xf bank_mask:0xf bound_ctrl:1
	s_nop 0
	v_add_f32_dpp v4, v4, v4 quad_perm:[1,0,3,2] row_mask:0xf bank_mask:0xf bound_ctrl:1
	v_add_f32_dpp v48, v48, v48 quad_perm:[1,0,3,2] row_mask:0xf bank_mask:0xf bound_ctrl:1
	s_nop 0
	v_mov_b32_dpp v6, v4 quad_perm:[2,3,0,1] row_mask:0xf bank_mask:0xf bound_ctrl:1
	v_mov_b32_dpp v50, v48 quad_perm:[2,3,0,1] row_mask:0xf bank_mask:0xf bound_ctrl:1
	s_and_saveexec_b64 s[2:3], s[36:37]
	v_add_f32_e32 v4, v4, v6
	v_add_f32_e32 v6, v48, v50
	ds_write2_b32 v15, v4, v6 offset0:8 offset1:40
	s_or_b64 exec, exec, s[2:3]
	v_cndmask_b32_e32 v67, 0, v5, vcc
	v_cndmask_b32_e64 v48, 0, v7, s[0:1]
	s_nop 0
	v_add_f32_dpp v4, v67, v67 row_half_mirror row_mask:0xf bank_mask:0xf bound_ctrl:1
	v_add_f32_dpp v6, v48, v48 row_half_mirror row_mask:0xf bank_mask:0xf bound_ctrl:1
	s_nop 0
	v_add_f32_dpp v4, v4, v4 quad_perm:[1,0,3,2] row_mask:0xf bank_mask:0xf bound_ctrl:1
	v_add_f32_dpp v6, v6, v6 quad_perm:[1,0,3,2] row_mask:0xf bank_mask:0xf bound_ctrl:1
	s_nop 0
	v_mov_b32_dpp v5, v4 quad_perm:[2,3,0,1] row_mask:0xf bank_mask:0xf bound_ctrl:1
	v_mov_b32_dpp v7, v6 quad_perm:[2,3,0,1] row_mask:0xf bank_mask:0xf bound_ctrl:1
	s_and_saveexec_b64 s[0:1], s[36:37]
	v_add_f32_e32 v4, v4, v5
	v_add_f32_e32 v5, v6, v7
	ds_write2_b32 v15, v4, v5 offset0:9 offset1:41
	s_or_b64 exec, exec, s[0:1]
	v_mov_b32_e32 v4, s80
	v_fma_f32 v5, v70, s33, -v4
	v_exp_f32_e32 v5, v5
	v_fma_f32 v4, v54, s33, -v4
	v_exp_f32_e32 v4, v4
	v_or_b32_e32 v6, 0xbf, v2
	v_mul_f32_e32 v5, v102, v5
	v_cmp_le_i32_e32 vcc, v6, v122
	v_mul_f32_e32 v4, v102, v4
	s_nop 0
	v_cndmask_b32_e32 v68, 0, v5, vcc
	v_or_b32_e32 v5, 0x2bf, v2
	v_cmp_le_i32_e32 vcc, v5, v122
	s_nop 1
	v_cndmask_b32_e32 v50, 0, v4, vcc
	v_add_f32_dpp v4, v68, v68 row_half_mirror row_mask:0xf bank_mask:0xf bound_ctrl:1
	s_nop 0
	v_add_f32_dpp v6, v50, v50 row_half_mirror row_mask:0xf bank_mask:0xf bound_ctrl:1
	v_add_f32_dpp v4, v4, v4 quad_perm:[1,0,3,2] row_mask:0xf bank_mask:0xf bound_ctrl:1
	s_nop 0
	v_add_f32_dpp v6, v6, v6 quad_perm:[1,0,3,2] row_mask:0xf bank_mask:0xf bound_ctrl:1
	v_mov_b32_dpp v5, v4 quad_perm:[2,3,0,1] row_mask:0xf bank_mask:0xf bound_ctrl:1
	s_nop 0
	v_mov_b32_dpp v7, v6 quad_perm:[2,3,0,1] row_mask:0xf bank_mask:0xf bound_ctrl:1
	s_and_saveexec_b64 s[0:1], s[36:37]
	v_add_f32_e32 v4, v4, v5
	v_add_f32_e32 v5, v6, v7
	ds_write2_b32 v15, v4, v5 offset0:10 offset1:42
	s_or_b64 exec, exec, s[0:1]
	v_mov_b32_e32 v4, s80
	v_fma_f32 v5, v71, s33, -v4
	v_exp_f32_e32 v5, v5
	v_fma_f32 v4, v55, s33, -v4
	v_exp_f32_e32 v4, v4
	v_add_u32_e32 v6, 0xcf, v2
	v_mul_f32_e32 v5, v102, v5
	v_cmp_le_i32_e32 vcc, v6, v122
	v_mul_f32_e32 v4, v102, v4
	s_nop 0
	v_cndmask_b32_e32 v69, 0, v5, vcc
	v_add_u32_e32 v5, 0x2cf, v2
	v_cmp_le_i32_e32 vcc, v5, v122
	s_nop 1
	v_cndmask_b32_e32 v53, 0, v4, vcc
	v_add_f32_dpp v4, v69, v69 row_half_mirror row_mask:0xf bank_mask:0xf bound_ctrl:1
	s_nop 0
	v_add_f32_dpp v6, v53, v53 row_half_mirror row_mask:0xf bank_mask:0xf bound_ctrl:1
	v_add_f32_dpp v4, v4, v4 quad_perm:[1,0,3,2] row_mask:0xf bank_mask:0xf bound_ctrl:1
	s_nop 0
	v_add_f32_dpp v6, v6, v6 quad_perm:[1,0,3,2] row_mask:0xf bank_mask:0xf bound_ctrl:1
	v_mov_b32_dpp v5, v4 quad_perm:[2,3,0,1] row_mask:0xf bank_mask:0xf bound_ctrl:1
	s_nop 0
	v_mov_b32_dpp v7, v6 quad_perm:[2,3,0,1] row_mask:0xf bank_mask:0xf bound_ctrl:1
	s_and_saveexec_b64 s[0:1], s[36:37]
	v_add_f32_e32 v4, v4, v5
	v_add_f32_e32 v5, v6, v7
	ds_write2_b32 v15, v4, v5 offset0:11 offset1:43
	s_or_b64 exec, exec, s[0:1]
	v_mov_b32_e32 v7, s80
	v_fma_f32 v4, v72, s33, -v7
	v_fma_f32 v6, v56, s33, -v7
	v_fma_f32 v5, v73, s33, -v7
	v_fma_f32 v7, v57, s33, -v7
	v_exp_f32_e32 v4, v4
	v_exp_f32_e32 v5, v5
	v_exp_f32_e32 v6, v6
	v_exp_f32_e32 v7, v7
	v_or_b32_e32 v51, 0x12f, v1
	v_or_b32_e32 v52, 0x11f, v2
	v_cmp_le_i32_e32 vcc, v51, v97
	v_or_b32_e32 v51, 0x31f, v2
	v_pk_mul_f32 v[4:5], v[102:103], v[4:5]
	v_cmp_le_i32_e64 s[0:1], v52, v122
	v_pk_mul_f32 v[6:7], v[102:103], v[6:7]
	v_cmp_le_i32_e64 s[2:3], v51, v122
	v_cndmask_b32_e64 v56, 0, v4, s[0:1]
	v_or_b32_e32 v4, 0x32f, v1
	v_cndmask_b32_e64 v51, 0, v6, s[2:3]
	v_cmp_le_i32_e64 s[0:1], v4, v97
	v_add_f32_dpp v4, v56, v56 row_half_mirror row_mask:0xf bank_mask:0xf bound_ctrl:1
	v_add_f32_dpp v52, v51, v51 row_half_mirror row_mask:0xf bank_mask:0xf bound_ctrl:1
	s_nop 0
	v_add_f32_dpp v4, v4, v4 quad_perm:[1,0,3,2] row_mask:0xf bank_mask:0xf bound_ctrl:1
	v_add_f32_dpp v52, v52, v52 quad_perm:[1,0,3,2] row_mask:0xf bank_mask:0xf bound_ctrl:1
	s_nop 0
	v_mov_b32_dpp v6, v4 quad_perm:[2,3,0,1] row_mask:0xf bank_mask:0xf bound_ctrl:1
	v_mov_b32_dpp v54, v52 quad_perm:[2,3,0,1] row_mask:0xf bank_mask:0xf bound_ctrl:1
	s_and_saveexec_b64 s[2:3], s[36:37]
	v_add_f32_e32 v4, v4, v6
	v_add_f32_e32 v6, v52, v54
	ds_write2_b32 v15, v4, v6 offset0:16 offset1:48
	s_or_b64 exec, exec, s[2:3]
	v_cndmask_b32_e32 v57, 0, v5, vcc
	v_cndmask_b32_e64 v52, 0, v7, s[0:1]
	s_nop 0
	v_add_f32_dpp v4, v57, v57 row_half_mirror row_mask:0xf bank_mask:0xf bound_ctrl:1
	v_add_f32_dpp v6, v52, v52 row_half_mirror row_mask:0xf bank_mask:0xf bound_ctrl:1
	s_nop 0
	v_add_f32_dpp v4, v4, v4 quad_perm:[1,0,3,2] row_mask:0xf bank_mask:0xf bound_ctrl:1
	v_add_f32_dpp v6, v6, v6 quad_perm:[1,0,3,2] row_mask:0xf bank_mask:0xf bound_ctrl:1
	s_nop 0
	v_mov_b32_dpp v5, v4 quad_perm:[2,3,0,1] row_mask:0xf bank_mask:0xf bound_ctrl:1
	v_mov_b32_dpp v7, v6 quad_perm:[2,3,0,1] row_mask:0xf bank_mask:0xf bound_ctrl:1
	s_and_saveexec_b64 s[0:1], s[36:37]
	v_add_f32_e32 v4, v4, v5
	v_add_f32_e32 v5, v6, v7
	ds_write2_b32 v15, v4, v5 offset0:17 offset1:49
	s_or_b64 exec, exec, s[0:1]
	v_mov_b32_e32 v4, s80
	v_fma_f32 v5, v74, s33, -v4
	v_exp_f32_e32 v5, v5
	v_fma_f32 v4, v58, s33, -v4
	v_exp_f32_e32 v4, v4
	v_or_b32_e32 v6, 0x13f, v2
	v_mul_f32_e32 v5, v102, v5
	v_cmp_le_i32_e32 vcc, v6, v122
	v_mul_f32_e32 v4, v102, v4
	s_nop 0
	v_cndmask_b32_e32 v58, 0, v5, vcc
	v_or_b32_e32 v5, 0x33f, v2
	v_cmp_le_i32_e32 vcc, v5, v122
	s_nop 1
	v_cndmask_b32_e32 v54, 0, v4, vcc
	v_add_f32_dpp v4, v58, v58 row_half_mirror row_mask:0xf bank_mask:0xf bound_ctrl:1
	s_nop 0
	v_add_f32_dpp v6, v54, v54 row_half_mirror row_mask:0xf bank_mask:0xf bound_ctrl:1
	v_add_f32_dpp v4, v4, v4 quad_perm:[1,0,3,2] row_mask:0xf bank_mask:0xf bound_ctrl:1
	s_nop 0
	v_add_f32_dpp v6, v6, v6 quad_perm:[1,0,3,2] row_mask:0xf bank_mask:0xf bound_ctrl:1
	v_mov_b32_dpp v5, v4 quad_perm:[2,3,0,1] row_mask:0xf bank_mask:0xf bound_ctrl:1
	s_nop 0
	v_mov_b32_dpp v7, v6 quad_perm:[2,3,0,1] row_mask:0xf bank_mask:0xf bound_ctrl:1
	s_and_saveexec_b64 s[0:1], s[36:37]
	v_add_f32_e32 v4, v4, v5
	v_add_f32_e32 v5, v6, v7
	ds_write2_b32 v15, v4, v5 offset0:18 offset1:50
	s_or_b64 exec, exec, s[0:1]
	v_mov_b32_e32 v4, s80
	v_fma_f32 v5, v75, s33, -v4
	v_exp_f32_e32 v5, v5
	v_fma_f32 v4, v59, s33, -v4
	v_exp_f32_e32 v4, v4
	v_add_u32_e32 v6, 0x14f, v2
	v_mul_f32_e32 v5, v102, v5
	v_cmp_le_i32_e32 vcc, v6, v122
	v_mul_f32_e32 v4, v102, v4
	s_nop 0
	v_cndmask_b32_e32 v59, 0, v5, vcc
	v_add_u32_e32 v5, 0x34f, v2
	v_cmp_le_i32_e32 vcc, v5, v122
	s_nop 1
	v_cndmask_b32_e32 v55, 0, v4, vcc
	v_add_f32_dpp v4, v59, v59 row_half_mirror row_mask:0xf bank_mask:0xf bound_ctrl:1
	s_nop 0
	v_add_f32_dpp v6, v55, v55 row_half_mirror row_mask:0xf bank_mask:0xf bound_ctrl:1
	v_add_f32_dpp v4, v4, v4 quad_perm:[1,0,3,2] row_mask:0xf bank_mask:0xf bound_ctrl:1
	s_nop 0
	v_add_f32_dpp v6, v6, v6 quad_perm:[1,0,3,2] row_mask:0xf bank_mask:0xf bound_ctrl:1
	v_mov_b32_dpp v5, v4 quad_perm:[2,3,0,1] row_mask:0xf bank_mask:0xf bound_ctrl:1
	s_nop 0
	v_mov_b32_dpp v7, v6 quad_perm:[2,3,0,1] row_mask:0xf bank_mask:0xf bound_ctrl:1
	s_and_saveexec_b64 s[0:1], s[36:37]
	v_add_f32_e32 v4, v4, v5
	v_add_f32_e32 v5, v6, v7
	ds_write2_b32 v15, v4, v5 offset0:19 offset1:51
	s_or_b64 exec, exec, s[0:1]
	v_mov_b32_e32 v7, s80
	v_fma_f32 v4, v76, s33, -v7
	v_fma_f32 v5, v77, s33, -v7
	v_exp_f32_e32 v4, v4
	v_exp_f32_e32 v5, v5
	v_fma_f32 v6, v60, s33, -v7
	v_fma_f32 v7, v61, s33, -v7
	v_exp_f32_e32 v6, v6
	v_exp_f32_e32 v7, v7
	v_or_b32_e32 v70, 0x19f, v2
	v_or_b32_e32 v60, 0x1af, v1
	v_pk_mul_f32 v[4:5], v[102:103], v[4:5]
	v_cmp_le_i32_e64 s[0:1], v70, v122
	v_cmp_le_i32_e32 vcc, v60, v97
	v_or_b32_e32 v1, 0x3af, v1
	v_cndmask_b32_e64 v60, 0, v4, s[0:1]
	v_or_b32_e32 v4, 0x39f, v2
	v_pk_mul_f32 v[6:7], v[102:103], v[6:7]
	v_cmp_le_i32_e64 s[2:3], v4, v122
	v_cmp_le_i32_e64 s[0:1], v1, v97
	v_add_f32_dpp v4, v60, v60 row_half_mirror row_mask:0xf bank_mask:0xf bound_ctrl:1
	v_cndmask_b32_e64 v1, 0, v6, s[2:3]
	s_nop 0
	v_add_f32_dpp v4, v4, v4 quad_perm:[1,0,3,2] row_mask:0xf bank_mask:0xf bound_ctrl:1
	v_add_f32_dpp v61, v1, v1 row_half_mirror row_mask:0xf bank_mask:0xf bound_ctrl:1
	s_nop 0
	v_mov_b32_dpp v6, v4 quad_perm:[2,3,0,1] row_mask:0xf bank_mask:0xf bound_ctrl:1
	v_add_f32_dpp v61, v61, v61 quad_perm:[1,0,3,2] row_mask:0xf bank_mask:0xf bound_ctrl:1
	s_nop 1
	v_mov_b32_dpp v70, v61 quad_perm:[2,3,0,1] row_mask:0xf bank_mask:0xf bound_ctrl:1
	s_and_saveexec_b64 s[2:3], s[36:37]
	v_add_f32_e32 v4, v4, v6
	v_add_f32_e32 v6, v61, v70
	ds_write2_b32 v15, v4, v6 offset0:24 offset1:56
	s_or_b64 exec, exec, s[2:3]
	v_cndmask_b32_e32 v6, 0, v5, vcc
	v_cndmask_b32_e64 v4, 0, v7, s[0:1]
	s_nop 0
	v_add_f32_dpp v5, v6, v6 row_half_mirror row_mask:0xf bank_mask:0xf bound_ctrl:1
	v_add_f32_dpp v61, v4, v4 row_half_mirror row_mask:0xf bank_mask:0xf bound_ctrl:1
	s_nop 0
	v_add_f32_dpp v5, v5, v5 quad_perm:[1,0,3,2] row_mask:0xf bank_mask:0xf bound_ctrl:1
	v_add_f32_dpp v61, v61, v61 quad_perm:[1,0,3,2] row_mask:0xf bank_mask:0xf bound_ctrl:1
	s_nop 0
	v_mov_b32_dpp v7, v5 quad_perm:[2,3,0,1] row_mask:0xf bank_mask:0xf bound_ctrl:1
	v_mov_b32_dpp v70, v61 quad_perm:[2,3,0,1] row_mask:0xf bank_mask:0xf bound_ctrl:1
	s_and_saveexec_b64 s[0:1], s[36:37]
	v_add_f32_e32 v5, v5, v7
	v_add_f32_e32 v7, v61, v70
	ds_write2_b32 v15, v5, v7 offset0:25 offset1:57
	s_or_b64 exec, exec, s[0:1]
	v_mov_b32_e32 v5, s80
	v_fma_f32 v7, v78, s33, -v5
	v_exp_f32_e32 v7, v7
	v_fma_f32 v5, v62, s33, -v5
	v_exp_f32_e32 v5, v5
	v_or_b32_e32 v61, 0x1bf, v2
	v_mul_f32_e32 v7, v102, v7
	v_cmp_le_i32_e32 vcc, v61, v122
	v_or_b32_e32 v61, 0x3bf, v2
	v_mul_f32_e32 v5, v102, v5
	v_cndmask_b32_e32 v7, 0, v7, vcc
	v_cmp_le_i32_e32 vcc, v61, v122
	s_nop 0
	v_add_f32_dpp v61, v7, v7 row_half_mirror row_mask:0xf bank_mask:0xf bound_ctrl:1
	v_cndmask_b32_e32 v5, 0, v5, vcc
	s_nop 0
	v_add_f32_dpp v61, v61, v61 quad_perm:[1,0,3,2] row_mask:0xf bank_mask:0xf bound_ctrl:1
	v_add_f32_dpp v70, v5, v5 row_half_mirror row_mask:0xf bank_mask:0xf bound_ctrl:1
	s_nop 0
	v_mov_b32_dpp v62, v61 quad_perm:[2,3,0,1] row_mask:0xf bank_mask:0xf bound_ctrl:1
	v_add_f32_dpp v70, v70, v70 quad_perm:[1,0,3,2] row_mask:0xf bank_mask:0xf bound_ctrl:1
	s_nop 1
	v_mov_b32_dpp v71, v70 quad_perm:[2,3,0,1] row_mask:0xf bank_mask:0xf bound_ctrl:1
	s_and_saveexec_b64 s[0:1], s[36:37]
	v_add_f32_e32 v61, v61, v62
	v_add_f32_e32 v62, v70, v71
	ds_write2_b32 v15, v61, v62 offset0:26 offset1:58
	s_or_b64 exec, exec, s[0:1]
	v_mov_b32_e32 v61, s80
	v_fma_f32 v62, v79, s33, -v61
	v_exp_f32_e32 v62, v62
	v_fma_f32 v61, v63, s33, -v61
	v_exp_f32_e32 v63, v61
	v_add_u32_e32 v70, 0x1cf, v2
	v_mul_f32_e32 v61, v102, v62
	v_cmp_le_i32_e32 vcc, v70, v122
	v_add_u32_e32 v2, 0x3cf, v2
	v_mul_f32_e32 v62, v102, v63
	v_cndmask_b32_e32 v61, 0, v61, vcc
	v_cmp_le_i32_e32 vcc, v2, v122
	s_nop 1
	v_cndmask_b32_e32 v2, 0, v62, vcc
	v_add_f32_dpp v62, v61, v61 row_half_mirror row_mask:0xf bank_mask:0xf bound_ctrl:1
	s_nop 0
	v_add_f32_dpp v70, v2, v2 row_half_mirror row_mask:0xf bank_mask:0xf bound_ctrl:1
	v_add_f32_dpp v62, v62, v62 quad_perm:[1,0,3,2] row_mask:0xf bank_mask:0xf bound_ctrl:1
	s_nop 0
	v_add_f32_dpp v70, v70, v70 quad_perm:[1,0,3,2] row_mask:0xf bank_mask:0xf bound_ctrl:1
	v_mov_b32_dpp v63, v62 quad_perm:[2,3,0,1] row_mask:0xf bank_mask:0xf bound_ctrl:1
	s_nop 0
	v_mov_b32_dpp v71, v70 quad_perm:[2,3,0,1] row_mask:0xf bank_mask:0xf bound_ctrl:1
	s_and_saveexec_b64 s[0:1], s[36:37]
	s_cbranch_execz .LBB0_266
	v_add_f32_e32 v62, v62, v63
	v_add_f32_e32 v63, v70, v71
	ds_write2_b32 v15, v62, v63 offset0:27 offset1:59
	s_branch .LBB0_266

.LBB0_313:
	v_readlane_b32 s0, v254, 45
	v_readlane_b32 s1, v254, 46
	s_movk_i32 s2, 0xc0
	v_lshlrev_b32_e32 v4, 2, v99
	v_mov_b64_e32 v[2:3], s[0:1]
	v_mad_u64_u32 v[2:3], s[0:1], v100, s2, v[2:3]
	v_mad_i32_i24 v3, v101, s2, v3
	v_mov_b32_e32 v5, v0
	v_lshl_add_u64 v[124:125], v[2:3], 0, v[4:5]
	s_waitcnt vmcnt(0) lgkmcnt(0)
	s_barrier
	global_load_dword v1, v[124:125], off
	global_load_dword v169, v[124:125], off offset:64
	s_waitcnt vmcnt(1)
	v_mul_f32_e32 v2, v32, v1
	v_mul_f32_e32 v3, v16, v1
	v_mul_f32_e32 v4, v33, v1
	v_mul_f32_e32 v5, v17, v1
	v_mul_f32_e32 v6, v34, v1
	v_mul_f32_e32 v7, v18, v1
	v_mul_f32_e32 v8, v35, v1
	v_mul_f32_e32 v9, v19, v1
	v_mul_f32_e32 v10, v36, v1
	v_mul_f32_e32 v11, v20, v1
	v_mul_f32_e32 v12, v37, v1
	v_mul_f32_e32 v13, v21, v1
	v_mul_f32_e32 v14, v38, v1
	v_mul_f32_e32 v15, v22, v1
	v_mul_f32_e32 v16, v39, v1
	v_mul_f32_e32 v17, v23, v1
	v_mul_f32_e32 v18, v40, v1
	v_mul_f32_e32 v19, v24, v1
	v_mul_f32_e32 v20, v41, v1
	v_mul_f32_e32 v21, v25, v1
	v_mul_f32_e32 v22, v42, v1
	v_mul_f32_e32 v23, v26, v1
	v_mul_f32_e32 v24, v43, v1
	v_mul_f32_e32 v25, v27, v1
	v_mul_f32_e32 v26, v44, v1
	v_mul_f32_e32 v27, v28, v1
	v_mul_f32_e32 v28, v45, v1
	v_mul_f32_e32 v29, v29, v1
	v_mul_f32_e32 v32, v46, v1
	v_mul_f32_e32 v30, v30, v1
	v_mul_f32_e32 v33, v47, v1
	v_mul_f32_e32 v1, v31, v1
	ds_write2st64_b32 v157, v2, v4 offset1:1
	ds_write2st64_b32 v157, v3, v5 offset0:16 offset1:17
	ds_write2st64_b32 v157, v6, v8 offset0:2 offset1:3
	ds_write2st64_b32 v157, v7, v9 offset0:18 offset1:19
	ds_write2st64_b32 v157, v10, v12 offset0:4 offset1:5
	ds_write2st64_b32 v157, v11, v13 offset0:20 offset1:21
	ds_write2st64_b32 v157, v14, v16 offset0:6 offset1:7
	ds_write2st64_b32 v157, v15, v17 offset0:22 offset1:23
	ds_write2st64_b32 v157, v18, v20 offset0:8 offset1:9
	ds_write2st64_b32 v157, v19, v21 offset0:24 offset1:25
	ds_write2st64_b32 v157, v22, v24 offset0:10 offset1:11
	ds_write2st64_b32 v157, v23, v25 offset0:26 offset1:27
	ds_write2st64_b32 v157, v26, v28 offset0:12 offset1:13
	ds_write2st64_b32 v157, v27, v29 offset0:28 offset1:29
	ds_write2st64_b32 v157, v32, v33 offset0:14 offset1:15
	ds_write2st64_b32 v157, v30, v1 offset0:30 offset1:31
	v_mov_b32_e32 v1, 0
	s_mov_b64 s[0:1], exec
	v_readlane_b32 s2, v254, 54
	v_readlane_b32 s3, v254, 55
	s_and_b64 s[2:3], s[0:1], s[2:3]
	s_mov_b64 exec, s[2:3]
	ds_read_b32 v1, v160
	s_or_b64 exec, exec, s[0:1]
	v_ashrrev_i32_e32 v2, 6, v176
	v_readlane_b32 s0, v254, 52
	v_add_u32_e32 v3, -1, v2
	v_cmp_eq_u32_e32 vcc, v146, v2
	v_readlane_b32 s1, v254, 53
	s_or_b64 s[0:1], s[0:1], vcc
	v_cmp_eq_u32_e32 vcc, v146, v3
	s_or_b64 s[0:1], s[0:1], vcc
	v_cmp_le_i32_e32 vcc, v146, v2
	s_and_b64 s[2:3], vcc, s[0:1]
	s_xor_b64 s[0:1], s[0:1], -1
	s_and_b64 s[54:55], vcc, s[0:1]
	v_cmp_eq_u32_e32 vcc, v158, v2
	v_cmp_eq_u32_e64 s[0:1], v158, v3
	s_or_b64 s[0:1], vcc, s[0:1]
	v_cmp_le_i32_e32 vcc, v158, v2
	ds_read_b128 v[2:5], v159
	ds_read2_b32 v[6:7], v161 offset0:1 offset1:2
	s_and_b64 s[6:7], vcc, s[0:1]
	s_xor_b64 s[0:1], s[0:1], -1
	s_and_b64 s[52:53], vcc, s[0:1]
	s_waitcnt lgkmcnt(1)
	v_fmac_f32_e32 v1, 2.0, v2
	v_fmac_f32_e32 v1, 2.0, v3
	ds_read2_b32 v[2:3], v171 offset1:1
	v_fmac_f32_e32 v1, 2.0, v4
	v_add_f32_e32 v1, v5, v1
	v_cndmask_b32_e64 v4, 0, v1, s[54:55]
	ds_read_b32 v1, v161 offset:12
	s_waitcnt lgkmcnt(1)
	v_fmac_f32_e32 v2, 2.0, v3
	v_fmac_f32_e32 v2, 2.0, v6
	v_fmac_f32_e32 v2, 2.0, v7
	s_xor_b64 s[8:9], s[2:3], -1
	s_waitcnt lgkmcnt(0)
	v_add_f32_e32 v1, v1, v2
	v_cndmask_b32_e64 v3, 0, v1, s[52:53]
	v_cndmask_b32_e64 v1, 0, 1, s[2:3]
	v_cmp_ne_u32_e32 vcc, 0, v1
	v_cndmask_b32_e64 v2, 0, 1, s[6:7]
	s_bcnt1_i32_b64 s0, vcc
	v_cmp_ne_u32_e32 vcc, 0, v2
	s_bcnt1_i32_b64 s1, vcc
	s_add_i32 s0, s0, s1
	s_mov_b32 s14, 0
	s_sub_i32 s15, 16, s0
	s_mov_b32 s0, 30
	s_mov_b32 s1, 0xc0000000
	v_and_b32_e32 v6, s1, v4
	v_and_b32_e32 v7, s1, v3
.LBB0_316:
	s_lshl_b32 s1, 1, s0
	s_or_b32 s4, s1, s14
	v_cmp_eq_u32_e64 s[2:3], s4, v6
	v_cmp_eq_u32_e64 s[10:11], s4, v7
	s_lshr_b32 s1, s1, 1
	s_sub_i32 s1, 0, s1
	v_and_b32_e32 v6, s1, v4
	v_and_b32_e32 v7, s1, v3
	s_bcnt1_i32_b64 s5, s[2:3]
	s_bcnt1_i32_b64 s1, s[10:11]
	s_add_i32 s1, s1, s5
	s_cmp_lt_i32 s1, s15
	s_cselect_b32 s1, s1, 0
	s_cselect_b32 s14, s14, s4
	s_sub_i32 s15, s15, s1
	s_add_i32 s0, s0, -1
	s_cmp_eq_u32 s0, -1
	s_cbranch_scc0 .LBB0_316
	v_cmp_eq_u32_e32 vcc, s14, v4
	v_cmp_eq_u32_e64 s[0:1], s14, v3
	s_and_b64 s[10:11], s[54:55], vcc
	v_cndmask_b32_e64 v5, 0, 1, s[10:11]
	s_and_b64 s[4:5], s[52:53], s[0:1]
	v_cmp_ne_u32_e32 vcc, 0, v5
	v_cndmask_b32_e64 v5, 0, 1, s[4:5]
	v_cmp_ne_u32_e64 s[0:1], 0, v5
	s_mov_b64 s[2:3], -1
	s_and_saveexec_b64 s[12:13], s[8:9]
	s_cbranch_execz .LBB0_319
	v_and_b32_e32 v6, vcc_lo, v118
	v_and_b32_e32 v5, vcc_hi, v115
	v_bcnt_u32_b32 v6, v6, 0
	v_bcnt_u32_b32 v5, v5, v6
	v_cmp_lt_u32_e64 s[2:3], s14, v4
	s_and_b64 s[16:17], s[54:55], s[2:3]
	v_cmp_gt_i32_e64 s[2:3], s15, v5
	s_and_b64 s[2:3], s[10:11], s[2:3]
	s_or_b64 s[2:3], s[16:17], s[2:3]
	s_orn2_b64 s[2:3], s[2:3], exec
.LBB0_319:
	s_or_b64 exec, exec, s[12:13]
	v_and_b32_e32 v5, s0, v118
	v_and_b32_e32 v4, s1, v115
	v_bcnt_u32_b32 v5, v5, 0
	s_bcnt1_i32_b64 s10, vcc
	v_bcnt_u32_b32 v4, v4, v5
	v_add_u32_e32 v4, s10, v4
	v_cmp_lt_u32_e32 vcc, s14, v3
	s_and_b64 s[0:1], s[52:53], vcc
	v_cmp_gt_i32_e32 vcc, s15, v4
	s_and_b64 s[4:5], s[4:5], vcc
	s_or_b64 s[0:1], s[6:7], s[0:1]
	v_cndmask_b32_e64 v3, 0, 1, s[2:3]
	s_or_b64 s[0:1], s[0:1], s[4:5]
	v_cmp_ne_u32_e32 vcc, 0, v3
	v_cndmask_b32_e64 v3, 0, 1, s[0:1]
	v_cmp_ne_u32_e64 s[50:51], 0, v3
	v_mov_b32_e32 v3, 0
	s_mov_b64 s[0:1], exec
	v_readlane_b32 s2, v254, 54
	v_readlane_b32 s3, v254, 55
	s_and_b64 s[2:3], s[0:1], s[2:3]
	s_mov_b64 exec, s[2:3]
	ds_read_b32 v3, v159 offset:2044
	s_or_b64 exec, exec, s[0:1]
	ds_read_b128 v[4:7], v159 offset:2048
	v_cmp_ne_u32_e64 s[0:1], 0, v1
	s_bcnt1_i32_b64 s2, s[0:1]
	v_cmp_ne_u32_e64 s[0:1], 0, v2
	s_bcnt1_i32_b64 s0, s[0:1]
	s_waitcnt lgkmcnt(0)
	v_fmac_f32_e32 v3, 2.0, v4
	v_add_u32_e32 v4, 0x7fc, v161
	v_fmac_f32_e32 v3, 2.0, v5
	ds_read2_b32 v[4:5], v4 offset1:1
	v_fmac_f32_e32 v3, 2.0, v6
	v_add_f32_e32 v3, v7, v3
	s_add_i32 s2, s2, s0
	s_mov_b32 s16, 0
	s_waitcnt lgkmcnt(0)
	v_fmac_f32_e32 v4, 2.0, v5
	v_add_u32_e32 v5, 0x804, v161
	ds_read2_b32 v[6:7], v5 offset1:1
	ds_read_b32 v5, v161 offset:2060
	v_cndmask_b32_e64 v3, 0, v3, s[54:55]
	s_sub_i32 s17, 16, s2
	s_mov_b32 s2, 30
	s_waitcnt lgkmcnt(1)
	v_fmac_f32_e32 v4, 2.0, v6
	v_fmac_f32_e32 v4, 2.0, v7
	s_waitcnt lgkmcnt(0)
	v_add_f32_e32 v4, v5, v4
	v_cndmask_b32_e64 v4, 0, v4, s[52:53]
	s_mov_b32 s4, 0xc0000000
	v_and_b32_e32 v6, s4, v3
	v_and_b32_e32 v7, s4, v4
.LBB0_322:
	s_lshl_b32 s0, 1, s2
	s_or_b32 s3, s0, s16
	v_cmp_eq_u32_e64 s[10:11], s3, v6
	v_cmp_eq_u32_e64 s[12:13], s3, v7
	s_lshr_b32 s4, s0, 1
	s_sub_i32 s4, 0, s4
	v_and_b32_e32 v6, s4, v3
	v_and_b32_e32 v7, s4, v4
	s_bcnt1_i32_b64 s5, s[10:11]
	s_bcnt1_i32_b64 s0, s[12:13]
	s_add_i32 s0, s0, s5
	s_cmp_lt_i32 s0, s17
	s_cselect_b32 s0, s0, 0
	s_cselect_b32 s16, s16, s3
	s_sub_i32 s17, s17, s0
	s_add_i32 s2, s2, -1
	s_cmp_lg_u32 s2, -1
	s_cbranch_scc1 .LBB0_322
	v_cmp_eq_u32_e64 s[0:1], s16, v3
	v_cmp_eq_u32_e64 s[2:3], s16, v4
	s_and_b64 s[12:13], s[54:55], s[0:1]
	v_cndmask_b32_e64 v5, 0, 1, s[12:13]
	s_and_b64 s[10:11], s[52:53], s[2:3]
	v_cmp_ne_u32_e64 s[0:1], 0, v5
	v_cndmask_b32_e64 v5, 0, 1, s[10:11]
	v_cmp_ne_u32_e64 s[2:3], 0, v5
	s_mov_b64 s[4:5], -1
	s_and_saveexec_b64 s[14:15], s[8:9]
	s_cbranch_execz .LBB0_325
	v_and_b32_e32 v6, s0, v118
	v_and_b32_e32 v5, s1, v115
	v_bcnt_u32_b32 v6, v6, 0
	v_bcnt_u32_b32 v5, v5, v6
	v_cmp_lt_u32_e64 s[4:5], s16, v3
	s_and_b64 s[18:19], s[54:55], s[4:5]
	v_cmp_gt_i32_e64 s[4:5], s17, v5
	s_and_b64 s[4:5], s[12:13], s[4:5]
	s_or_b64 s[4:5], s[18:19], s[4:5]
	s_orn2_b64 s[4:5], s[4:5], exec
.LBB0_325:
	s_or_b64 exec, exec, s[14:15]
	v_and_b32_e32 v5, s2, v118
	v_and_b32_e32 v3, s3, v115
	v_bcnt_u32_b32 v5, v5, 0
	s_bcnt1_i32_b64 s0, s[0:1]
	v_bcnt_u32_b32 v3, v3, v5
	v_add_u32_e32 v3, s0, v3
	v_cmp_lt_u32_e64 s[0:1], s16, v4
	s_and_b64 s[2:3], s[52:53], s[0:1]
	v_cmp_gt_i32_e64 s[0:1], s17, v3
	s_and_b64 s[0:1], s[10:11], s[0:1]
	s_or_b64 s[2:3], s[6:7], s[2:3]
	v_cndmask_b32_e64 v3, 0, 1, s[4:5]
	s_or_b64 s[0:1], s[2:3], s[0:1]
	v_cmp_ne_u32_e64 s[56:57], 0, v3
	v_cndmask_b32_e64 v3, 0, 1, s[0:1]
	v_cmp_ne_u32_e64 s[58:59], 0, v3
	v_mov_b32_e32 v3, 0
	s_mov_b64 s[0:1], exec
	v_readlane_b32 s2, v254, 54
	v_readlane_b32 s3, v254, 55
	s_and_b64 s[2:3], s[0:1], s[2:3]
	s_mov_b64 exec, s[2:3]
	ds_read_b32 v3, v159 offset:4092
	s_or_b64 exec, exec, s[0:1]
	ds_read_b128 v[4:7], v159 offset:4096
	v_cmp_ne_u32_e64 s[0:1], 0, v1
	s_bcnt1_i32_b64 s2, s[0:1]
	v_cmp_ne_u32_e64 s[0:1], 0, v2
	s_bcnt1_i32_b64 s0, s[0:1]
	s_waitcnt lgkmcnt(0)
	v_fmac_f32_e32 v3, 2.0, v4
	v_add_u32_e32 v4, 0xffc, v161
	v_fmac_f32_e32 v3, 2.0, v5
	ds_read2_b32 v[4:5], v4 offset1:1
	v_fmac_f32_e32 v3, 2.0, v6
	v_add_f32_e32 v3, v7, v3
	s_add_i32 s2, s2, s0
	s_mov_b32 s16, 0
	s_waitcnt lgkmcnt(0)
	v_fmac_f32_e32 v4, 2.0, v5
	v_add_u32_e32 v5, 0x1004, v161
	ds_read2_b32 v[6:7], v5 offset1:1
	ds_read_b32 v5, v161 offset:4108
	v_cndmask_b32_e64 v3, 0, v3, s[54:55]
	s_sub_i32 s17, 16, s2
	s_mov_b32 s2, 30
	s_waitcnt lgkmcnt(1)
	v_fmac_f32_e32 v4, 2.0, v6
	v_fmac_f32_e32 v4, 2.0, v7
	s_waitcnt lgkmcnt(0)
	v_add_f32_e32 v4, v5, v4
	v_cndmask_b32_e64 v4, 0, v4, s[52:53]
	s_mov_b32 s4, 0xc0000000
	v_and_b32_e32 v6, s4, v3
	v_and_b32_e32 v7, s4, v4

.LBB0_331:
	s_or_b64 exec, exec, s[14:15]
	v_and_b32_e32 v5, s2, v118
	v_and_b32_e32 v3, s3, v115
	v_bcnt_u32_b32 v5, v5, 0
	s_bcnt1_i32_b64 s0, s[0:1]
	v_bcnt_u32_b32 v3, v3, v5
	v_add_u32_e32 v3, s0, v3
	v_cmp_lt_u32_e64 s[0:1], s16, v4
	s_and_b64 s[2:3], s[52:53], s[0:1]
	v_cmp_gt_i32_e64 s[0:1], s17, v3
	s_and_b64 s[0:1], s[10:11], s[0:1]
	s_or_b64 s[2:3], s[6:7], s[2:3]
	v_cndmask_b32_e64 v3, 0, 1, s[4:5]
	s_or_b64 s[0:1], s[2:3], s[0:1]
	v_cmp_ne_u32_e64 s[60:61], 0, v3
	v_cndmask_b32_e64 v3, 0, 1, s[0:1]
	v_cmp_ne_u32_e64 s[62:63], 0, v3
	v_mov_b32_e32 v3, 0
	s_mov_b64 s[0:1], exec
	v_readlane_b32 s2, v254, 54
	v_readlane_b32 s3, v254, 55
	s_and_b64 s[2:3], s[0:1], s[2:3]
	s_mov_b64 exec, s[2:3]
	ds_read_b32 v3, v159 offset:6140
	s_or_b64 exec, exec, s[0:1]
	ds_read_b128 v[4:7], v159 offset:6144
	v_cmp_ne_u32_e64 s[0:1], 0, v1
	s_bcnt1_i32_b64 s2, s[0:1]
	v_cmp_ne_u32_e64 s[0:1], 0, v2
	s_bcnt1_i32_b64 s0, s[0:1]
	s_waitcnt lgkmcnt(0)
	v_fmac_f32_e32 v3, 2.0, v4
	v_add_u32_e32 v4, 0x17fc, v161
	v_fmac_f32_e32 v3, 2.0, v5
	ds_read2_b32 v[4:5], v4 offset1:1
	v_fmac_f32_e32 v3, 2.0, v6
	v_add_f32_e32 v3, v7, v3
	s_add_i32 s2, s2, s0
	s_mov_b32 s16, 0
	s_waitcnt lgkmcnt(0)
	v_fmac_f32_e32 v4, 2.0, v5
	v_add_u32_e32 v5, 0x1804, v161
	ds_read2_b32 v[6:7], v5 offset1:1
	ds_read_b32 v5, v161 offset:6156
	v_cndmask_b32_e64 v3, 0, v3, s[54:55]
	s_sub_i32 s17, 16, s2
	s_mov_b32 s2, 30
	s_waitcnt lgkmcnt(1)
	v_fmac_f32_e32 v4, 2.0, v6
	v_fmac_f32_e32 v4, 2.0, v7
	s_waitcnt lgkmcnt(0)
	v_add_f32_e32 v4, v5, v4
	v_cndmask_b32_e64 v4, 0, v4, s[52:53]
	s_mov_b32 s4, 0xc0000000
	v_and_b32_e32 v6, s4, v3
	v_and_b32_e32 v7, s4, v4
.LBB0_334:
	s_lshl_b32 s0, 1, s2
	s_or_b32 s3, s0, s16
	v_cmp_eq_u32_e64 s[10:11], s3, v6
	v_cmp_eq_u32_e64 s[12:13], s3, v7
	s_lshr_b32 s4, s0, 1
	s_sub_i32 s4, 0, s4
	v_and_b32_e32 v6, s4, v3
	v_and_b32_e32 v7, s4, v4
	s_bcnt1_i32_b64 s5, s[10:11]
	s_bcnt1_i32_b64 s0, s[12:13]
	s_add_i32 s0, s0, s5
	s_cmp_lt_i32 s0, s17
	s_cselect_b32 s0, s0, 0
	s_cselect_b32 s16, s16, s3
	s_sub_i32 s17, s17, s0
	s_add_i32 s2, s2, -1
	s_cmp_lg_u32 s2, -1
	s_cbranch_scc1 .LBB0_334
	v_cmp_eq_u32_e64 s[0:1], s16, v3
	v_cmp_eq_u32_e64 s[2:3], s16, v4
	s_and_b64 s[12:13], s[54:55], s[0:1]
	v_cndmask_b32_e64 v1, 0, 1, s[12:13]
	s_and_b64 s[10:11], s[52:53], s[2:3]
	v_cmp_ne_u32_e64 s[0:1], 0, v1
	v_cndmask_b32_e64 v1, 0, 1, s[10:11]
	v_cmp_ne_u32_e64 s[2:3], 0, v1
	s_mov_b64 s[4:5], -1
	s_and_saveexec_b64 s[14:15], s[8:9]
	s_cbranch_execz .LBB0_337
	v_and_b32_e32 v2, s0, v118
	v_and_b32_e32 v1, s1, v115
	v_bcnt_u32_b32 v2, v2, 0
	v_bcnt_u32_b32 v1, v1, v2
	v_cmp_lt_u32_e64 s[4:5], s16, v3
	s_and_b64 s[8:9], s[54:55], s[4:5]
	v_cmp_gt_i32_e64 s[4:5], s17, v1
	s_and_b64 s[4:5], s[12:13], s[4:5]
	s_or_b64 s[4:5], s[8:9], s[4:5]
	s_orn2_b64 s[4:5], s[4:5], exec
